# attA diagonal pair: causal mask rewritten as one inline-constant compare + one select per score register with three rotating lane-mask registers (no hazard nops, no per-register index adds); otherwise
# baseline (speedup 1.0000x reference)
; #define LAS __attribute__((address_space(3)))
; __device__ __forceinline__ int crow(int r, int hi) { return (r & 3) + 8 * (r >> 2) + 4 * hi; }
; #define MFMA32(a, b, c) __builtin_amdgcn_mfma_f32_32x32x16_bf16((a), (b), (c), 0, 0, 0)
; __device__ __forceinline__ void unit(LAS unsigned char* lds, bf16_t* P1, const bf16_t* vaT, int b, int h, int qblk, float lam, const float* subln_w, const float* khalf) {
;     ...
;         { typedef int i32x4 __attribute__((ext_vector_type(4)));
;           const i32x4 fa = *(const LAS i32x4*)(lds + 4 * STG + (jj & 1) * 32), fb = *(const LAS i32x4*)(lds + 4 * STG + (jj & 1) * 32 + 16);
;           if (((fa[0] + fa[1]) + (fa[2] + fa[3])) + ((fb[0] + fb[1]) + (fb[2] + fb[3])) == 8) break; }
;         if (jj + 3 < NT) { DMA_TILE(j - 3, (stg + 3) & 3); }
;         const LAS unsigned char* kb = lds + stg * STG;
;         stg = (stg + 1) & 3;
;         f32x16 S0, S1;
;         { float slv = sl2; asm volatile("" : "+v"(slv));
; #pragma unroll
;           for (int r = 0; r < 16; ++r) { S0[r] = __builtin_fmaf(slv, (float)((r & 3) + 8 * (r >> 2)), sl2h); S1[r] = S0[r]; } }
; #pragma unroll
;         for (int ks = 0; ks < 4; ++ks) {
;             const bf16x8 a0 = *(const LAS bf16x8*)(kb + koff[ks]);
;             const bf16x8 a1 = *(const LAS bf16x8*)(kb + koff[ks] + 32 * 256);
;             S0 = MFMA32(a0, qf[ks], S0); S1 = MFMA32(a1, qf[ks], S1);
;         }
;         const int kv0 = 64 * j;
;         if (j >= NT - 2) {
; #pragma unroll
;             for (int r = 0; r < 16; ++r) { const int kv = kv0 + crow(r, hi); if (kv > qrow) S0[r] = -INFINITY; if (kv + 32 > qrow) S1[r] = -INFINITY; }
;         }
;         const float tb0 = sl2 * (float)(kv0 - qrow), tb1 = tb0 + sl2 * 32.f;
;         float mx0 = S0[0], mx1 = S1[0];
; #pragma unroll
;         for (int r = 1; r < 16; ++r) { mx0 = fmaxf(mx0, S0[r]); mx1 = fmaxf(mx1, S1[r]); }
;         float mt = fmaxf(mx0 + tb0, mx1 + tb1); mt = fmaxf(mt, __shfl_xor(mt, 32));
;         const bool skip = __all((mt < m - 24.f) || (mt == -INFINITY));
.La_after_bar0:
	s_lshl_b32 s82, s80, 15
	s_add_i32 s83, s82, 0x8000
	s_sub_i32 s100, s76, 64
	s_and_b32 s2, s81, 2
	s_lshl_b32 s2, s2, 4
	s_add_i32 s2, s2, 0x20000
	v_mov_b32_e32 v70, s2
	ds_read_b128 v[66:69], v70
	ds_read_b128 v[70:73], v70 offset:16
	v_add3_u32 v201, s82, v129, v151
	v_add3_u32 v135, s82, v185, v151
	v_add3_u32 v249, s82, v186, v151
	v_add3_u32 v254, s82, v187, v151
	ds_read_b128 v[192:195], v201
	ds_read_b128 v[202:205], v135
	ds_read_b128 v[210:213], v249
	ds_read_b128 v[218:221], v254
	ds_read_b128 v[196:199], v201 offset:8192
	ds_read_b128 v[206:209], v135 offset:8192
	ds_read_b128 v[214:217], v249 offset:8192
	ds_read_b128 v[222:225], v254 offset:8192
	s_waitcnt lgkmcnt(8)
	v_add3_u32 v66, v66, v67, v68
	v_add3_u32 v69, v69, v70, v71
	v_add_u32_e32 v72, v72, v73
	v_add3_u32 v66, v66, v69, v72
	v_cmp_eq_u32_e32 vcc, 8, v66
	s_cbranch_vccnz .LBB0_420
	s_waitcnt lgkmcnt(4)
	v_mfma_f32_32x32x16_bf16 v[82:97], v[192:195], v[98:101], v[226:241]
	v_add_u32_e32 v244, s82, v168
	v_add_u32_e32 v245, s82, v169
	v_mfma_f32_32x32x16_bf16 v[82:97], v[202:205], v[102:105], v[82:97]
	v_add_u32_e32 v246, s82, v170
	v_add_u32_e32 v247, s82, v171
	v_mfma_f32_32x32x16_bf16 v[82:97], v[210:213], v[106:109], v[82:97]
	v_add_f32_e32 v143, v133, v121
	v_max_f32_e32 v143, 0xff7fffff, v143
	v_mfma_f32_32x32x16_bf16 v[82:97], v[218:221], v[110:113], v[82:97]
	ds_read_b128 v[192:195], v244 offset:16384
	ds_read_b128 v[202:205], v244 offset:20480
	ds_read_b128 v[210:213], v244 offset:24576
	ds_read_b128 v[218:221], v244 offset:28672
	s_waitcnt lgkmcnt(4)
	v_mfma_f32_32x32x16_bf16 v[66:81], v[196:199], v[98:101], v[226:241]
	v_mfma_f32_32x32x16_bf16 v[66:81], v[206:209], v[102:105], v[66:81]
	v_max3_f32 v0, v82, v83, v84
	v_max3_f32 v0, v0, v85, v86
	v_mfma_f32_32x32x16_bf16 v[66:81], v[214:217], v[106:109], v[66:81]
	v_max3_f32 v0, v0, v87, v88
	v_max3_f32 v0, v0, v89, v90
	v_max3_f32 v0, v0, v91, v92
	v_mfma_f32_32x32x16_bf16 v[66:81], v[222:225], v[110:113], v[66:81]
	v_max3_f32 v0, v0, v93, v94
	v_max3_f32 v0, v0, v95, v96
	v_max_f32_e32 v0, v0, v97
	ds_read_b128 v[196:199], v245 offset:16384
	ds_read_b128 v[206:209], v245 offset:20480
	ds_read_b128 v[214:217], v245 offset:24576
	ds_read_b128 v[222:225], v245 offset:28672
	s_nop 3
	v_add_u32_e32 v243, s76, v189
	v_sub_u32_e32 v243, v125, v243
	v_subrev_u32_e32 v243, 64, v243
	v_cmp_le_i32_e64 vcc, 0, v243
	v_cmp_le_i32_e64 s[2:3], 1, v243
	v_cmp_le_i32_e64 s[4:5], 2, v243
	v_cndmask_b32_e64 v82, v184, v82, vcc
	v_cmp_le_i32_e64 vcc, 3, v243
	v_cndmask_b32_e64 v83, v184, v83, s[2:3]
	v_cmp_le_i32_e64 s[2:3], 8, v243
	v_cndmask_b32_e64 v84, v184, v84, s[4:5]
	v_cmp_le_i32_e64 s[4:5], 9, v243
	v_cndmask_b32_e64 v85, v184, v85, vcc
	v_cmp_le_i32_e64 vcc, 10, v243
	v_cndmask_b32_e64 v86, v184, v86, s[2:3]
	v_cmp_le_i32_e64 s[2:3], 11, v243
	v_cndmask_b32_e64 v87, v184, v87, s[4:5]
	v_cmp_le_i32_e64 s[4:5], 16, v243
	v_cndmask_b32_e64 v88, v184, v88, vcc
	v_cmp_le_i32_e64 vcc, 17, v243
	v_cndmask_b32_e64 v89, v184, v89, s[2:3]
	v_cmp_le_i32_e64 s[2:3], 18, v243
	v_cndmask_b32_e64 v90, v184, v90, s[4:5]
	v_cmp_le_i32_e64 s[4:5], 19, v243
	v_cndmask_b32_e64 v91, v184, v91, vcc
	v_cmp_le_i32_e64 vcc, 24, v243
	v_cndmask_b32_e64 v92, v184, v92, s[2:3]
	v_cmp_le_i32_e64 s[2:3], 25, v243
	v_cndmask_b32_e64 v93, v184, v93, s[4:5]
	v_cmp_le_i32_e64 s[4:5], 26, v243
	v_cndmask_b32_e64 v94, v184, v94, vcc
	v_cmp_le_i32_e64 vcc, 27, v243
	v_cndmask_b32_e64 v95, v184, v95, s[2:3]
	v_cmp_le_i32_e64 s[2:3], 32, v243
	v_cndmask_b32_e64 v96, v184, v96, s[4:5]
	v_cmp_le_i32_e64 s[4:5], 33, v243
	v_cndmask_b32_e64 v97, v184, v97, vcc
	v_cmp_le_i32_e64 vcc, 34, v243
	v_cndmask_b32_e64 v66, v184, v66, s[2:3]
	v_cmp_le_i32_e64 s[2:3], 35, v243
	v_cndmask_b32_e64 v67, v184, v67, s[4:5]
	v_cmp_le_i32_e64 s[4:5], 40, v243
	v_cndmask_b32_e64 v68, v184, v68, vcc
	v_cmp_le_i32_e64 vcc, 41, v243
	v_cndmask_b32_e64 v69, v184, v69, s[2:3]
	v_cmp_le_i32_e64 s[2:3], 42, v243
	v_cndmask_b32_e64 v70, v184, v70, s[4:5]
	v_cmp_le_i32_e64 s[4:5], 43, v243
	v_cndmask_b32_e64 v71, v184, v71, vcc
	v_cmp_le_i32_e64 vcc, 48, v243
	v_cndmask_b32_e64 v72, v184, v72, s[2:3]
	v_cmp_le_i32_e64 s[2:3], 49, v243
	v_cndmask_b32_e64 v73, v184, v73, s[4:5]
	v_cmp_le_i32_e64 s[4:5], 50, v243
	v_cndmask_b32_e64 v74, v184, v74, vcc
	v_cmp_le_i32_e64 vcc, 51, v243
	v_cndmask_b32_e64 v75, v184, v75, s[2:3]
	v_cmp_le_i32_e64 s[2:3], 56, v243
	v_cndmask_b32_e64 v76, v184, v76, s[4:5]
	v_cmp_le_i32_e64 s[4:5], 57, v243
	v_cndmask_b32_e64 v77, v184, v77, vcc
	v_cmp_le_i32_e64 vcc, 58, v243
	v_cndmask_b32_e64 v78, v184, v78, s[2:3]
	v_cmp_le_i32_e64 s[2:3], 59, v243
	v_cndmask_b32_e64 v79, v184, v79, s[4:5]
	v_cndmask_b32_e64 v80, v184, v80, vcc
	v_cndmask_b32_e64 v81, v184, v81, s[2:3]
	v_max3_f32 v0, v82, v83, v84
	v_max3_f32 v0, v0, v85, v86
	v_max3_f32 v0, v0, v87, v88
	v_max3_f32 v0, v0, v89, v90
	v_max3_f32 v0, v0, v91, v92
	v_max3_f32 v0, v0, v93, v94
	v_max3_f32 v0, v0, v95, v96
	v_max_f32_e32 v0, v0, v97
	s_nop 1
	v_max3_f32 v120, v66, v67, v68
	v_max3_f32 v120, v120, v69, v70
	v_max3_f32 v120, v120, v71, v72
	v_max3_f32 v120, v120, v73, v74
	v_max3_f32 v120, v120, v75, v76
	v_max3_f32 v120, v120, v77, v78
	v_max3_f32 v120, v120, v79, v80
	v_max_f32_e32 v120, v120, v81
	v_add_f32_e32 v120, v188, v120
	v_max_f32_e32 v0, v0, v120
	v_add_f32_e32 v0, v132, v0
	v_mov_b32_e32 v120, v0
	s_nop 1
	v_permlane32_swap_b32_e32 v0, v120
	v_max_f32_e32 v0, v0, v120
	v_cmp_lt_f32_e32 vcc, v0, v143
	v_max_f32_e32 v133, v133, v0
	v_mov_b32_e32 v255, v0
	s_andn2_b64 s[2:3], exec, vcc
	s_cbranch_scc0 .La_skipA0
; #define LAS __attribute__((address_space(3)))
; __device__ __forceinline__ unsigned cvtpk(float lo, float hi) { return pg8::cvt_pk_bf16(lo, hi); }
; __device__ __forceinline__ float ex2(float v) { return __builtin_amdgcn_exp2f(v); }
; #define MFMA32(a, b, c) __builtin_amdgcn_mfma_f32_32x32x16_bf16((a), (b), (c), 0, 0, 0)
; __device__ __forceinline__ void unit(LAS unsigned char* lds, bf16_t* P1, const bf16_t* vaT, int b, int h, int qblk, float lam, const float* subln_w, const float* khalf) {
;     ...
;         const float mn = fmaxf(m, mt); const float alpha = ex2(m - mn); m = mn;
;         const float c0 = tb0 - mn, c1 = tb1 - mn;
;         f32x2 ps2 = (f32x2){0.f, 0.f};
; #pragma unroll
;         for (int r = 0; r < 16; r += 2) { f32x2 a = (f32x2){S0[r], S0[r + 1]} + c0, bq = (f32x2){S1[r], S1[r + 1]} + c1;
;             a.x = ex2(a.x); a.y = ex2(a.y); bq.x = ex2(bq.x); bq.y = ex2(bq.y); S0[r] = a.x; S0[r + 1] = a.y; S1[r] = bq.x; S1[r + 1] = bq.y; ps2 = ps2 + a; ps2 = ps2 + bq; }
;         l = l * alpha + (ps2.x + ps2.y);
;         if (__any(alpha != 1.f)) {
; #pragma unroll
;             for (int d = 0; d < 4; ++d) O[d] = O[d] * alpha;
;         }
;         u32x4 pk[2][2];
; #pragma unroll
;         for (int s = 0; s < 2; ++s) {
;             pk[0][s] = (u32x4){cvtpk(S0[8 * s + 0], S0[8 * s + 1]), cvtpk(S0[8 * s + 2], S0[8 * s + 3]), cvtpk(S0[8 * s + 4], S0[8 * s + 5]), cvtpk(S0[8 * s + 6], S0[8 * s + 7])};
;             pk[1][s] = (u32x4){cvtpk(S1[8 * s + 0], S1[8 * s + 1]), cvtpk(S1[8 * s + 2], S1[8 * s + 3]), cvtpk(S1[8 * s + 4], S1[8 * s + 5]), cvtpk(S1[8 * s + 6], S1[8 * s + 7])};
;         }
; #pragma unroll
;         for (int d = 0; d < 4; ++d)
; #pragma unroll
;             for (int t2 = 0; t2 < 2; ++t2)
; #pragma unroll
;                 for (int s = 0; s < 2; ++s) {
;                     const bf16x8 vf = *(const LAS bf16x8*)(kb + voff[2 * t2 + s] + d * 32 * 128);
;                     O[d] = MFMA32(vf, __builtin_bit_cast(bf16x8, pk[t2][s]), O[d]);
;                 }
	v_exp_f32_e32 v82, v82
	v_exp_f32_e32 v83, v83
	v_exp_f32_e32 v84, v84
	v_exp_f32_e32 v85, v85
	v_exp_f32_e32 v86, v86
	v_exp_f32_e32 v87, v87
	v_exp_f32_e32 v88, v88
	v_exp_f32_e32 v89, v89
	v_add_f32_e32 v252, v82, v84
	v_add_f32_e32 v253, v83, v85
	v_cvt_pk_bf16_f32 v82, v82, v83
	v_cvt_pk_bf16_f32 v83, v84, v85
	v_cvt_pk_bf16_f32 v84, v86, v87
	v_cvt_pk_bf16_f32 v85, v88, v89
	v_add_f32_e32 v252, v252, v86
	v_add_f32_e32 v253, v253, v87
	v_add_f32_e32 v252, v252, v88
	v_add_f32_e32 v253, v253, v89
	s_waitcnt lgkmcnt(4)
	v_mfma_f32_32x32x16_bf16 v[50:65], v[192:195], v[82:85], v[50:65]
	ds_read_b128 v[192:195], v246 offset:16384
	v_exp_f32_e32 v90, v90
	v_exp_f32_e32 v91, v91
	v_exp_f32_e32 v92, v92
	v_exp_f32_e32 v93, v93
	v_exp_f32_e32 v94, v94
	v_mfma_f32_32x32x16_bf16 v[34:49], v[202:205], v[82:85], v[34:49]
	ds_read_b128 v[202:205], v246 offset:20480
	v_exp_f32_e32 v95, v95
	v_exp_f32_e32 v96, v96
	v_exp_f32_e32 v97, v97
	v_add_f32_e32 v252, v252, v90
	v_add_f32_e32 v253, v253, v91
	v_mfma_f32_32x32x16_bf16 v[18:33], v[210:213], v[82:85], v[18:33]
	ds_read_b128 v[210:213], v246 offset:24576
	v_add_f32_e32 v252, v252, v92
	v_add_f32_e32 v253, v253, v93
	v_cvt_pk_bf16_f32 v90, v90, v91
	v_cvt_pk_bf16_f32 v91, v92, v93
	v_cvt_pk_bf16_f32 v92, v94, v95
	v_mfma_f32_32x32x16_bf16 v[2:17], v[218:221], v[82:85], v[2:17]
	ds_read_b128 v[218:221], v246 offset:28672
	v_cvt_pk_bf16_f32 v93, v96, v97
	v_add_f32_e32 v252, v252, v94
	v_add_f32_e32 v253, v253, v95
	v_add_f32_e32 v252, v252, v96
	v_add_f32_e32 v253, v253, v97
	s_waitcnt lgkmcnt(4)
	v_mfma_f32_32x32x16_bf16 v[50:65], v[196:199], v[90:93], v[50:65]
	ds_read_b128 v[196:199], v247 offset:16384
	v_add_f32_e32 v66, v188, v66
	v_add_f32_e32 v67, v188, v67
	v_add_f32_e32 v68, v188, v68
	v_add_f32_e32 v69, v188, v69
	v_add_f32_e32 v70, v188, v70
	v_add_f32_e32 v71, v188, v71
	v_add_f32_e32 v72, v188, v72
	v_mfma_f32_32x32x16_bf16 v[34:49], v[206:209], v[90:93], v[34:49]
	ds_read_b128 v[206:209], v247 offset:20480
	v_add_f32_e32 v73, v188, v73
	v_exp_f32_e32 v66, v66
	v_exp_f32_e32 v67, v67
	v_exp_f32_e32 v68, v68
	v_exp_f32_e32 v69, v69
	v_exp_f32_e32 v70, v70
	v_exp_f32_e32 v71, v71
	v_mfma_f32_32x32x16_bf16 v[18:33], v[214:217], v[90:93], v[18:33]
	ds_read_b128 v[214:217], v247 offset:24576
	v_exp_f32_e32 v72, v72
	v_exp_f32_e32 v73, v73
	v_add_f32_e32 v252, v252, v66
	v_add_f32_e32 v253, v253, v67
	v_add_f32_e32 v252, v252, v68
	v_add_f32_e32 v253, v253, v69
	v_cvt_pk_bf16_f32 v66, v66, v67
	v_mfma_f32_32x32x16_bf16 v[2:17], v[222:225], v[90:93], v[2:17]
	ds_read_b128 v[222:225], v247 offset:28672
	v_cvt_pk_bf16_f32 v67, v68, v69
	v_cvt_pk_bf16_f32 v68, v70, v71
	v_cvt_pk_bf16_f32 v69, v72, v73
	v_add_f32_e32 v252, v252, v70
	v_add_f32_e32 v253, v253, v71
	v_add_f32_e32 v252, v252, v72
	v_add_f32_e32 v253, v253, v73
	s_waitcnt lgkmcnt(4)
	v_mfma_f32_32x32x16_bf16 v[50:65], v[192:195], v[66:69], v[50:65]
	v_add_f32_e32 v74, v188, v74
	v_add_f32_e32 v75, v188, v75
	v_add_f32_e32 v76, v188, v76
	v_add_f32_e32 v77, v188, v77
	v_add_f32_e32 v78, v188, v78
	v_add_f32_e32 v79, v188, v79
	v_add_f32_e32 v80, v188, v80
	v_mfma_f32_32x32x16_bf16 v[34:49], v[202:205], v[66:69], v[34:49]
	v_add_f32_e32 v81, v188, v81
	v_exp_f32_e32 v74, v74
	v_exp_f32_e32 v75, v75
	v_exp_f32_e32 v76, v76
	v_exp_f32_e32 v77, v77
	v_exp_f32_e32 v78, v78
	v_exp_f32_e32 v79, v79
	v_mfma_f32_32x32x16_bf16 v[18:33], v[210:213], v[66:69], v[18:33]
	v_exp_f32_e32 v80, v80
	v_exp_f32_e32 v81, v81
	v_add_f32_e32 v252, v252, v74
	v_add_f32_e32 v253, v253, v75
	v_add_f32_e32 v252, v252, v76
	v_add_f32_e32 v253, v253, v77
	v_cvt_pk_bf16_f32 v74, v74, v75
	v_mfma_f32_32x32x16_bf16 v[2:17], v[218:221], v[66:69], v[2:17]
	v_cvt_pk_bf16_f32 v75, v76, v77
	v_cvt_pk_bf16_f32 v76, v78, v79
	v_cvt_pk_bf16_f32 v77, v80, v81
	v_add_f32_e32 v252, v252, v78
	v_add_f32_e32 v253, v253, v79
	v_add_f32_e32 v252, v252, v80
	v_add_f32_e32 v253, v253, v81
	s_waitcnt lgkmcnt(0)
	v_mfma_f32_32x32x16_bf16 v[50:65], v[196:199], v[74:77], v[50:65]
	v_add_f32_e32 v250, v252, v253
	v_add_f32_e32 v191, v191, v250
	v_add_f32_e32 v226, v131, v226
	v_add_f32_e32 v227, v131, v227
	v_add_f32_e32 v228, v131, v228
	v_mfma_f32_32x32x16_bf16 v[34:49], v[206:209], v[74:77], v[34:49]
	v_add_f32_e32 v229, v131, v229
	v_add_f32_e32 v230, v131, v230
	v_add_f32_e32 v231, v131, v231
	v_add_f32_e32 v232, v131, v232
	v_add_f32_e32 v233, v131, v233
	v_mfma_f32_32x32x16_bf16 v[18:33], v[214:217], v[74:77], v[18:33]
	v_add_f32_e32 v234, v131, v234
	v_add_f32_e32 v235, v131, v235
	v_add_f32_e32 v236, v131, v236
	v_add_f32_e32 v237, v131, v237
	v_add_f32_e32 v238, v131, v238
	v_mfma_f32_32x32x16_bf16 v[2:17], v[222:225], v[74:77], v[2:17]
	v_add_f32_e32 v239, v131, v239
	v_add_f32_e32 v240, v131, v240
	v_add_f32_e32 v241, v131, v241

; __device__ __forceinline__ int crow(int r, int hi) { return (r & 3) + 8 * (r >> 2) + 4 * hi; }
; __device__ __forceinline__ void unit(LAS unsigned char* lds, bf16_t* P1, const bf16_t* vaT, int b, int h, int qblk, float lam, const float* subln_w, const float* khalf) {
;     ...
;         const int kv0 = 64 * j;
;         if (j >= NT - 2) {
; #pragma unroll
;             for (int r = 0; r < 16; ++r) { const int kv = kv0 + crow(r, hi); if (kv > qrow) S0[r] = -INFINITY; if (kv + 32 > qrow) S1[r] = -INFINITY; }
;         }
;         const float tb0 = sl2 * (float)(kv0 - qrow), tb1 = tb0 + sl2 * 32.f;
;         float mx0 = S0[0], mx1 = S1[0];
; #pragma unroll
;         for (int r = 1; r < 16; ++r) { mx0 = fmaxf(mx0, S0[r]); mx1 = fmaxf(mx1, S1[r]); }
;         float mt = fmaxf(mx0 + tb0, mx1 + tb1); mt = fmaxf(mt, __shfl_xor(mt, 32));
;         const bool skip = __all((mt < m - 24.f) || (mt == -INFINITY));
.La_qk_doneB0:
	ds_read_b128 v[196:199], v245 offset:49152
	ds_read_b128 v[206:209], v245 offset:53248
	ds_read_b128 v[214:217], v245 offset:57344
	ds_read_b128 v[222:225], v245 offset:61440
	s_nop 3
	v_add_u32_e32 v243, s100, v189
	v_sub_u32_e32 v243, v125, v243
	v_subrev_u32_e32 v243, 64, v243
	v_cmp_le_i32_e64 vcc, 0, v243
	v_cmp_le_i32_e64 s[2:3], 1, v243
	v_cmp_le_i32_e64 s[4:5], 2, v243
	v_cndmask_b32_e64 v82, v184, v82, vcc
	v_cmp_le_i32_e64 vcc, 3, v243
	v_cndmask_b32_e64 v83, v184, v83, s[2:3]
	v_cmp_le_i32_e64 s[2:3], 8, v243
	v_cndmask_b32_e64 v84, v184, v84, s[4:5]
	v_cmp_le_i32_e64 s[4:5], 9, v243
	v_cndmask_b32_e64 v85, v184, v85, vcc
	v_cmp_le_i32_e64 vcc, 10, v243
	v_cndmask_b32_e64 v86, v184, v86, s[2:3]
	v_cmp_le_i32_e64 s[2:3], 11, v243
	v_cndmask_b32_e64 v87, v184, v87, s[4:5]
	v_cmp_le_i32_e64 s[4:5], 16, v243
	v_cndmask_b32_e64 v88, v184, v88, vcc
	v_cmp_le_i32_e64 vcc, 17, v243
	v_cndmask_b32_e64 v89, v184, v89, s[2:3]
	v_cmp_le_i32_e64 s[2:3], 18, v243
	v_cndmask_b32_e64 v90, v184, v90, s[4:5]
	v_cmp_le_i32_e64 s[4:5], 19, v243
	v_cndmask_b32_e64 v91, v184, v91, vcc
	v_cmp_le_i32_e64 vcc, 24, v243
	v_cndmask_b32_e64 v92, v184, v92, s[2:3]
	v_cmp_le_i32_e64 s[2:3], 25, v243
	v_cndmask_b32_e64 v93, v184, v93, s[4:5]
	v_cmp_le_i32_e64 s[4:5], 26, v243
	v_cndmask_b32_e64 v94, v184, v94, vcc
	v_cmp_le_i32_e64 vcc, 27, v243
	v_cndmask_b32_e64 v95, v184, v95, s[2:3]
	v_cmp_le_i32_e64 s[2:3], 32, v243
	v_cndmask_b32_e64 v96, v184, v96, s[4:5]
	v_cmp_le_i32_e64 s[4:5], 33, v243
	v_cndmask_b32_e64 v97, v184, v97, vcc
	v_cmp_le_i32_e64 vcc, 34, v243
	v_cndmask_b32_e64 v66, v184, v66, s[2:3]
	v_cmp_le_i32_e64 s[2:3], 35, v243
	v_cndmask_b32_e64 v67, v184, v67, s[4:5]
	v_cmp_le_i32_e64 s[4:5], 40, v243
	v_cndmask_b32_e64 v68, v184, v68, vcc
	v_cmp_le_i32_e64 vcc, 41, v243
	v_cndmask_b32_e64 v69, v184, v69, s[2:3]
	v_cmp_le_i32_e64 s[2:3], 42, v243
	v_cndmask_b32_e64 v70, v184, v70, s[4:5]
	v_cmp_le_i32_e64 s[4:5], 43, v243
	v_cndmask_b32_e64 v71, v184, v71, vcc
	v_cmp_le_i32_e64 vcc, 48, v243
	v_cndmask_b32_e64 v72, v184, v72, s[2:3]
	v_cmp_le_i32_e64 s[2:3], 49, v243
	v_cndmask_b32_e64 v73, v184, v73, s[4:5]
	v_cmp_le_i32_e64 s[4:5], 50, v243
	v_cndmask_b32_e64 v74, v184, v74, vcc
	v_cmp_le_i32_e64 vcc, 51, v243
	v_cndmask_b32_e64 v75, v184, v75, s[2:3]
	v_cmp_le_i32_e64 s[2:3], 56, v243
	v_cndmask_b32_e64 v76, v184, v76, s[4:5]
	v_cmp_le_i32_e64 s[4:5], 57, v243
	v_cndmask_b32_e64 v77, v184, v77, vcc
	v_cmp_le_i32_e64 vcc, 58, v243
	v_cndmask_b32_e64 v78, v184, v78, s[2:3]
	v_cmp_le_i32_e64 s[2:3], 59, v243
	v_cndmask_b32_e64 v79, v184, v79, s[4:5]
	v_cndmask_b32_e64 v80, v184, v80, vcc
	v_cndmask_b32_e64 v81, v184, v81, s[2:3]
	v_max3_f32 v0, v82, v83, v84
	v_max3_f32 v0, v0, v85, v86
	v_max3_f32 v0, v0, v87, v88
	v_max3_f32 v0, v0, v89, v90
	v_max3_f32 v0, v0, v91, v92
	v_max3_f32 v0, v0, v93, v94
	v_max3_f32 v0, v0, v95, v96
	v_max_f32_e32 v0, v0, v97
	s_nop 1
	v_max3_f32 v120, v66, v67, v68
	v_max3_f32 v120, v120, v69, v70
	v_max3_f32 v120, v120, v71, v72
	v_max3_f32 v120, v120, v73, v74
	v_max3_f32 v120, v120, v75, v76
	v_max3_f32 v120, v120, v77, v78
	v_max3_f32 v120, v120, v79, v80
	v_max_f32_e32 v120, v120, v81
	v_add_f32_e32 v120, v188, v120
	v_max_f32_e32 v0, v0, v120
	v_add_f32_e32 v0, v132, v0
	v_mov_b32_e32 v120, v0
	s_nop 1
	v_permlane32_swap_b32_e32 v0, v120
	v_max_f32_e32 v0, v0, v120
	v_cmp_lt_f32_e32 vcc, v0, v143
	v_max_f32_e32 v133, v133, v0
	v_mov_b32_e32 v255, v0
	s_andn2_b64 s[2:3], exec, vcc
	s_cbranch_scc0 .La_skipB0
; #define LAS __attribute__((address_space(3)))
; __device__ __forceinline__ unsigned cvtpk(float lo, float hi) { return pg8::cvt_pk_bf16(lo, hi); }
; __device__ __forceinline__ float ex2(float v) { return __builtin_amdgcn_exp2f(v); }
; #define MFMA32(a, b, c) __builtin_amdgcn_mfma_f32_32x32x16_bf16((a), (b), (c), 0, 0, 0)
; __device__ __forceinline__ void unit(LAS unsigned char* lds, bf16_t* P1, const bf16_t* vaT, int b, int h, int qblk, float lam, const float* subln_w, const float* khalf) {
;     ...
;         { float slv = sl2; asm volatile("" : "+v"(slv));
; #pragma unroll
;           for (int r = 0; r < 16; ++r) { S0[r] = __builtin_fmaf(slv, (float)((r & 3) + 8 * (r >> 2)), sl2h); S1[r] = S0[r]; } }
;     ...
;         const float mn = fmaxf(m, mt); const float alpha = ex2(m - mn); m = mn;
;         const float c0 = tb0 - mn, c1 = tb1 - mn;
;         f32x2 ps2 = (f32x2){0.f, 0.f};
; #pragma unroll
;         for (int r = 0; r < 16; r += 2) { f32x2 a = (f32x2){S0[r], S0[r + 1]} + c0, bq = (f32x2){S1[r], S1[r + 1]} + c1;
;             a.x = ex2(a.x); a.y = ex2(a.y); bq.x = ex2(bq.x); bq.y = ex2(bq.y); S0[r] = a.x; S0[r + 1] = a.y; S1[r] = bq.x; S1[r + 1] = bq.y; ps2 = ps2 + a; ps2 = ps2 + bq; }
;         l = l * alpha + (ps2.x + ps2.y);
;         if (__any(alpha != 1.f)) {
; #pragma unroll
;             for (int d = 0; d < 4; ++d) O[d] = O[d] * alpha;
;         }
;         u32x4 pk[2][2];
; #pragma unroll
;         for (int s = 0; s < 2; ++s) {
;             pk[0][s] = (u32x4){cvtpk(S0[8 * s + 0], S0[8 * s + 1]), cvtpk(S0[8 * s + 2], S0[8 * s + 3]), cvtpk(S0[8 * s + 4], S0[8 * s + 5]), cvtpk(S0[8 * s + 6], S0[8 * s + 7])};
;             pk[1][s] = (u32x4){cvtpk(S1[8 * s + 0], S1[8 * s + 1]), cvtpk(S1[8 * s + 2], S1[8 * s + 3]), cvtpk(S1[8 * s + 4], S1[8 * s + 5]), cvtpk(S1[8 * s + 6], S1[8 * s + 7])};
;         }
; #pragma unroll
;         for (int d = 0; d < 4; ++d)
; #pragma unroll
;             for (int t2 = 0; t2 < 2; ++t2)
; #pragma unroll
;                 for (int s = 0; s < 2; ++s) {
;                     const bf16x8 vf = *(const LAS bf16x8*)(kb + voff[2 * t2 + s] + d * 32 * 128);
;                     O[d] = MFMA32(vf, __builtin_bit_cast(bf16x8, pk[t2][s]), O[d]);
;                 }
	v_exp_f32_e32 v82, v82
	v_exp_f32_e32 v83, v83
	v_exp_f32_e32 v84, v84
	v_exp_f32_e32 v85, v85
	v_exp_f32_e32 v86, v86
	v_exp_f32_e32 v87, v87
	v_exp_f32_e32 v88, v88
	v_exp_f32_e32 v89, v89
	v_add_f32_e32 v252, v82, v84
	v_add_f32_e32 v253, v83, v85
	v_cvt_pk_bf16_f32 v82, v82, v83
	v_cvt_pk_bf16_f32 v83, v84, v85
	v_cvt_pk_bf16_f32 v84, v86, v87
	v_cvt_pk_bf16_f32 v85, v88, v89
	v_add_f32_e32 v252, v252, v86
	v_add_f32_e32 v253, v253, v87
	v_add_f32_e32 v252, v252, v88
	v_add_f32_e32 v253, v253, v89
	s_waitcnt lgkmcnt(4)
	v_mfma_f32_32x32x16_bf16 v[50:65], v[192:195], v[82:85], v[50:65]
	ds_read_b128 v[192:195], v246 offset:49152
	v_exp_f32_e32 v90, v90
	v_exp_f32_e32 v91, v91
	v_exp_f32_e32 v92, v92
	v_exp_f32_e32 v93, v93
	v_exp_f32_e32 v94, v94
	v_mfma_f32_32x32x16_bf16 v[34:49], v[202:205], v[82:85], v[34:49]
	ds_read_b128 v[202:205], v246 offset:53248
	v_exp_f32_e32 v95, v95
	v_exp_f32_e32 v96, v96
	v_exp_f32_e32 v97, v97
	v_add_f32_e32 v252, v252, v90
	v_add_f32_e32 v253, v253, v91
	v_mfma_f32_32x32x16_bf16 v[18:33], v[210:213], v[82:85], v[18:33]
	ds_read_b128 v[210:213], v246 offset:57344
	v_add_f32_e32 v252, v252, v92
	v_add_f32_e32 v253, v253, v93
	v_cvt_pk_bf16_f32 v90, v90, v91
	v_cvt_pk_bf16_f32 v91, v92, v93
	v_cvt_pk_bf16_f32 v92, v94, v95
	v_mfma_f32_32x32x16_bf16 v[2:17], v[218:221], v[82:85], v[2:17]
	ds_read_b128 v[218:221], v246 offset:61440
	v_cvt_pk_bf16_f32 v93, v96, v97
	v_add_f32_e32 v252, v252, v94
	v_add_f32_e32 v253, v253, v95
	v_add_f32_e32 v252, v252, v96
	v_add_f32_e32 v253, v253, v97
	s_waitcnt lgkmcnt(4)
	v_mfma_f32_32x32x16_bf16 v[50:65], v[196:199], v[90:93], v[50:65]
	ds_read_b128 v[196:199], v247 offset:49152
	v_add_f32_e32 v66, v188, v66
	v_add_f32_e32 v67, v188, v67
	v_add_f32_e32 v68, v188, v68
	v_add_f32_e32 v69, v188, v69
	v_add_f32_e32 v70, v188, v70
	v_add_f32_e32 v71, v188, v71
	v_add_f32_e32 v72, v188, v72
	v_mfma_f32_32x32x16_bf16 v[34:49], v[206:209], v[90:93], v[34:49]
	ds_read_b128 v[206:209], v247 offset:53248
	v_add_f32_e32 v73, v188, v73
	v_exp_f32_e32 v66, v66
	v_exp_f32_e32 v67, v67
	v_exp_f32_e32 v68, v68
	v_exp_f32_e32 v69, v69
	v_exp_f32_e32 v70, v70
	v_exp_f32_e32 v71, v71
	v_mfma_f32_32x32x16_bf16 v[18:33], v[214:217], v[90:93], v[18:33]
	ds_read_b128 v[214:217], v247 offset:57344
	v_exp_f32_e32 v72, v72
	v_exp_f32_e32 v73, v73
	v_add_f32_e32 v252, v252, v66
	v_add_f32_e32 v253, v253, v67
	v_add_f32_e32 v252, v252, v68
	v_add_f32_e32 v253, v253, v69
	v_cvt_pk_bf16_f32 v66, v66, v67
	v_mfma_f32_32x32x16_bf16 v[2:17], v[222:225], v[90:93], v[2:17]
	ds_read_b128 v[222:225], v247 offset:61440
	v_cvt_pk_bf16_f32 v67, v68, v69
	v_cvt_pk_bf16_f32 v68, v70, v71
	v_cvt_pk_bf16_f32 v69, v72, v73
	v_add_f32_e32 v252, v252, v70
	v_add_f32_e32 v253, v253, v71
	v_add_f32_e32 v252, v252, v72
	v_add_f32_e32 v253, v253, v73
	s_waitcnt lgkmcnt(4)
	v_mfma_f32_32x32x16_bf16 v[50:65], v[192:195], v[66:69], v[50:65]
	v_add_f32_e32 v74, v188, v74
	v_add_f32_e32 v75, v188, v75
	v_add_f32_e32 v76, v188, v76
	v_add_f32_e32 v77, v188, v77
	v_add_f32_e32 v78, v188, v78
	v_add_f32_e32 v79, v188, v79
	v_add_f32_e32 v80, v188, v80
	v_mfma_f32_32x32x16_bf16 v[34:49], v[202:205], v[66:69], v[34:49]
	v_add_f32_e32 v81, v188, v81
	v_exp_f32_e32 v74, v74
	v_exp_f32_e32 v75, v75
	v_exp_f32_e32 v76, v76
	v_exp_f32_e32 v77, v77
	v_exp_f32_e32 v78, v78
	v_exp_f32_e32 v79, v79
	v_mfma_f32_32x32x16_bf16 v[18:33], v[210:213], v[66:69], v[18:33]
	v_exp_f32_e32 v80, v80
	v_exp_f32_e32 v81, v81
	v_add_f32_e32 v252, v252, v74
	v_add_f32_e32 v253, v253, v75
	v_add_f32_e32 v252, v252, v76
	v_add_f32_e32 v253, v253, v77
	v_cvt_pk_bf16_f32 v74, v74, v75
	v_mfma_f32_32x32x16_bf16 v[2:17], v[218:221], v[66:69], v[2:17]
	v_cvt_pk_bf16_f32 v75, v76, v77
	v_cvt_pk_bf16_f32 v76, v78, v79
	v_cvt_pk_bf16_f32 v77, v80, v81
	v_add_f32_e32 v252, v252, v78
	v_add_f32_e32 v253, v253, v79
	v_add_f32_e32 v252, v252, v80
	v_add_f32_e32 v253, v253, v81
	s_waitcnt lgkmcnt(0)
	v_mfma_f32_32x32x16_bf16 v[50:65], v[196:199], v[74:77], v[50:65]
	v_add_f32_e32 v250, v252, v253
	v_add_f32_e32 v191, v191, v250
	v_add_f32_e32 v248, 0xc3000000, v137
	v_fma_f32 v248, v127, v248, -v132
	v_add_f32_e32 v248, v130, v248
	v_mov_b32_e32 v226, v248
	v_mfma_f32_32x32x16_bf16 v[34:49], v[206:209], v[74:77], v[34:49]
	v_add_f32_e32 v227, v248, v127
	v_fma_f32 v228, v127, s22, v248
	v_fma_f32 v229, v127, s23, v248
	v_fma_f32 v230, v127, s24, v248
	v_fma_f32 v231, v127, s25, v248
	v_fma_f32 v232, v127, s26, v248
	v_mfma_f32_32x32x16_bf16 v[18:33], v[214:217], v[74:77], v[18:33]
	v_fma_f32 v233, v127, s27, v248
	v_fma_f32 v234, v127, s28, v248
	v_fma_f32 v235, v127, s29, v248
	v_fma_f32 v236, v127, s30, v248
	v_fma_f32 v237, v127, s31, v248
	v_fma_f32 v238, v127, s34, v248
	v_mfma_f32_32x32x16_bf16 v[2:17], v[222:225], v[74:77], v[2:17]
	v_fma_f32 v239, v127, s35, v248
	v_fma_f32 v240, v127, s36, v248
	v_fma_f32 v241, v127, s37, v248
